# v38 + the per-unit prefetch block also touches the same eight rows of XC
# baseline (speedup 1.0000x reference)
.Lpf_a_go:
	s_add_u32 s26, s28, s99
	s_addc_u32 s27, s29, 0
	s_add_u32 s26, s26, s60
	s_addc_u32 s27, s27, 0
	v_mbcnt_hi_u32_b32 v46, -1, v185
	v_lshrrev_b32_e32 v45, 1, v46
	v_and_b32_e32 v47, 1, v46
	v_mul_lo_u32 v45, v45, s98
	v_mul_lo_u32 v46, v46, s98
	v_lshl_add_u32 v45, v47, 7, v45
	s_lshl_b32 s100, s98, 5
	s_add_u32 s58, s26, s61
	s_addc_u32 s59, s27, 0
	global_load_dword v44, v45, s[58:59]
	s_add_u32 s58, s58, s100
	s_addc_u32 s59, s59, 0
	global_load_dword v44, v45, s[58:59]
	s_add_u32 s58, s58, s100
	s_addc_u32 s59, s59, 0
	global_load_dword v44, v45, s[58:59]
	s_add_u32 s58, s58, s100
	s_addc_u32 s59, s59, 0
	global_load_dword v44, v45, s[58:59]
	s_add_u32 s58, s26, s73
	s_addc_u32 s59, s27, 0
	global_load_dword v44, v45, s[58:59]
	s_add_u32 s58, s58, s100
	s_addc_u32 s59, s59, 0
	global_load_dword v44, v45, s[58:59]
	s_add_u32 s58, s58, s100
	s_addc_u32 s59, s59, 0
	global_load_dword v44, v45, s[58:59]
	s_add_u32 s58, s58, s100
	s_addc_u32 s59, s59, 0
	global_load_dword v44, v45, s[58:59]
	s_add_u32 s58, s26, s72
	s_addc_u32 s59, s27, 0
	global_load_dword v44, v46, s[58:59]
	s_lshl_b32 s100, s100, 1
	s_add_u32 s58, s58, s100
	s_addc_u32 s59, s59, 0
	global_load_dword v44, v46, s[58:59]
	s_mul_i32 s58, s101, 0x18000
	s_add_u32 s26, s28, 0x8501000
	s_addc_u32 s27, s29, 0
	s_add_u32 s26, s26, s58
	s_addc_u32 s27, s27, 0
	v_mbcnt_hi_u32_b32 v47, -1, v185
	v_lshlrev_b32_e32 v47, 6, v47
	global_load_dword v44, v47, s[26:27]
	s_add_u32 s26, s26, 0x3000
	s_addc_u32 s27, s27, 0
	global_load_dword v44, v47, s[26:27]
	s_add_u32 s26, s26, 0x3000
	s_addc_u32 s27, s27, 0
	global_load_dword v44, v47, s[26:27]
	s_add_u32 s26, s26, 0x3000
	s_addc_u32 s27, s27, 0
	global_load_dword v44, v47, s[26:27]
	s_add_u32 s26, s26, 0x3000
	s_addc_u32 s27, s27, 0
	global_load_dword v44, v47, s[26:27]
	s_add_u32 s26, s26, 0x3000
	s_addc_u32 s27, s27, 0
	global_load_dword v44, v47, s[26:27]
	s_add_u32 s26, s26, 0x3000
	s_addc_u32 s27, s27, 0
	global_load_dword v44, v47, s[26:27]
	s_add_u32 s26, s26, 0x3000
	s_addc_u32 s27, s27, 0
	global_load_dword v44, v47, s[26:27]
	s_lshl_b32 s58, s101, 15
	s_add_u32 s26, s28, 0xe500000
	s_addc_u32 s27, s29, 0
	s_add_u32 s26, s26, s58
	s_addc_u32 s27, s27, 0
	global_load_dword v44, v47, s[26:27]
	s_add_u32 s26, s26, 0x1000
	s_addc_u32 s27, s27, 0
	global_load_dword v44, v47, s[26:27]
	s_add_u32 s26, s26, 0x1000
	s_addc_u32 s27, s27, 0
	global_load_dword v44, v47, s[26:27]
	s_add_u32 s26, s26, 0x1000
	s_addc_u32 s27, s27, 0
	global_load_dword v44, v47, s[26:27]
	s_add_u32 s26, s26, 0x1000
	s_addc_u32 s27, s27, 0
	global_load_dword v44, v47, s[26:27]
	s_add_u32 s26, s26, 0x1000
	s_addc_u32 s27, s27, 0
	global_load_dword v44, v47, s[26:27]
	s_add_u32 s26, s26, 0x1000
	s_addc_u32 s27, s27, 0
	global_load_dword v44, v47, s[26:27]
	s_add_u32 s26, s26, 0x1000
	s_addc_u32 s27, s27, 0
	global_load_dword v44, v47, s[26:27]

.Lpf_b_end:
	s_branch .LBB0_631
	s_nop 0
	s_nop 0
	s_nop 0
	s_nop 0
	s_nop 0
	s_nop 0
	s_nop 0
	s_nop 0
	s_nop 0
	s_nop 0
	s_nop 0
	s_nop 0
	s_nop 0
	s_nop 0
	s_nop 0
	s_nop 0
	s_nop 0
	s_nop 0
	s_nop 0
	s_nop 0
	s_nop 0
	s_nop 0
	s_nop 0
	s_nop 0
	s_nop 0
	s_nop 0
	s_nop 0
	s_nop 0
	s_nop 0
	s_nop 0
	s_nop 0
	s_nop 0
	s_nop 0
	s_nop 0
	s_nop 0
	s_nop 0
	s_nop 0
	s_nop 0
	s_nop 0
	s_nop 0
	s_nop 0
	s_nop 0
	s_nop 0
	s_nop 0
	s_nop 0
	s_nop 0
	s_nop 0
	s_nop 0
	s_nop 0
	s_nop 0
	s_nop 0
	s_nop 0
	s_nop 0
	s_nop 0
	s_nop 0
	s_nop 0
	s_nop 0
	s_nop 0
	s_nop 0
	s_nop 0
	s_nop 0
	s_nop 0
	s_nop 0
	s_nop 0
	s_nop 0
	s_nop 0
	s_nop 0
	s_nop 0
	s_nop 0
	s_nop 0
	s_nop 0
	s_nop 0
	s_nop 0
	s_nop 0
	s_nop 0
	s_nop 0
	s_nop 0
	s_nop 0
	s_nop 0
	s_nop 0
	s_nop 0
	s_nop 0
	s_nop 0
	s_nop 0
	s_nop 0
	s_nop 0
	s_nop 0
	s_nop 0
	s_nop 0
	s_nop 0
	s_nop 0
	s_nop 0
	s_nop 0
	s_nop 0
	s_nop 0
	s_nop 0
	s_nop 0
	s_nop 0
	s_nop 0
	s_nop 0
	s_nop 0
	s_nop 0
	s_nop 0
	s_nop 0
	s_nop 0
	s_nop 0
	s_nop 0
	s_nop 0
	s_nop 0
	s_nop 0
	s_nop 0
	s_nop 0
	s_nop 0
	s_nop 0
	s_nop 0
	s_nop 0
	s_nop 0
	s_nop 0
	s_nop 0
	s_nop 0
	s_nop 0
	s_nop 0
	s_nop 0
	s_nop 0
	s_nop 0
	s_nop 0
	s_nop 0
	s_nop 0
	s_nop 0
	s_nop 0
	s_nop 0
	s_nop 0
	s_nop 0
	s_nop 0
	s_nop 0
	s_nop 0
	s_nop 0
	s_nop 0
	s_nop 0
	s_nop 0
	s_nop 0
	s_nop 0
	s_nop 0
	s_nop 0
	s_nop 0
	s_nop 0
	s_nop 0
	s_nop 0
	s_nop 0
	s_nop 0
	s_nop 0
	s_nop 0
	s_nop 0
	s_nop 0
	s_nop 0
	s_nop 0
	s_nop 0
	s_nop 0
	s_nop 0
	s_nop 0
	s_nop 0
	s_nop 0
	s_nop 0
	s_nop 0
	s_nop 0
	s_nop 0
	s_nop 0
	s_nop 0
	s_nop 0
	s_nop 0
	s_nop 0
	s_nop 0
	s_nop 0
	s_nop 0
	s_nop 0
	s_nop 0
	s_nop 0
	s_nop 0
	s_nop 0
	s_nop 0
	s_nop 0
	s_nop 0
	s_nop 0
	s_nop 0
	s_nop 0
	s_nop 0
	s_nop 0
	s_nop 0
	s_nop 0
	s_nop 0
	s_nop 0
	s_nop 0
	s_nop 0
	s_nop 0
	s_nop 0
	s_nop 0
	s_nop 0
	s_nop 0
	s_nop 0
	s_nop 0
	s_nop 0
	s_nop 0
	s_nop 0
	s_nop 0
	s_nop 0
	s_nop 0
	s_nop 0
	s_nop 0
	s_nop 0
	s_nop 0
	s_nop 0
	s_nop 0
	s_nop 0
	s_nop 0
	s_nop 0
	s_nop 0
	s_nop 0
	s_nop 0
	s_nop 0
	s_nop 0
	s_nop 0
	s_nop 0
	s_nop 0
	s_nop 0
	s_nop 0
	s_nop 0
	s_nop 0
	s_nop 0
	s_nop 0
	s_nop 0
	s_nop 0
	s_nop 0
	s_nop 0
	s_nop 0
	s_nop 0
	s_nop 0
	s_nop 0
	s_nop 0
	s_nop 0
	s_nop 0
	s_nop 0
	s_nop 0
	s_nop 0
	s_nop 0
	s_nop 0
	s_nop 0
	s_nop 0
	s_nop 0
	s_nop 0
	s_nop 0
	s_nop 0
	s_nop 0
	s_nop 0
	s_nop 0
	s_nop 0
	s_nop 0
	s_nop 0
	s_nop 0
	s_nop 0
	s_nop 0
	s_nop 0
	s_nop 0
	s_nop 0
	s_nop 0
	s_nop 0
	s_nop 0
	s_nop 0
	s_nop 0
	s_nop 0
	s_nop 0
	s_nop 0
	s_nop 0
	s_nop 0
	s_nop 0
	s_nop 0
	s_nop 0
	s_nop 0
	s_nop 0
	s_nop 0
	s_nop 0
	s_nop 0
	s_nop 0
	s_nop 0
	s_nop 0
	s_nop 0
	s_nop 0
	s_nop 0
	s_nop 0
	s_nop 0
	s_nop 0
	s_nop 0
	s_nop 0
	s_nop 0
	s_nop 0
	s_nop 0
	s_nop 0
	s_nop 0
	s_nop 0
	s_nop 0
	s_nop 0
	s_nop 0
	s_nop 0
	s_nop 0
	s_nop 0
	s_nop 0
	s_nop 0
	s_nop 0
	s_nop 0
	s_nop 0
	s_nop 0
	s_nop 0
	s_nop 0
	s_nop 0
	s_nop 0
	s_nop 0
	s_nop 0
	s_nop 0
	s_nop 0
	s_nop 0
	s_nop 0
	s_nop 0
	s_nop 0
	s_nop 0
	s_nop 0
	s_nop 0
	s_nop 0
	s_nop 0
	s_nop 0
	s_nop 0
	s_nop 0
	s_nop 0
	s_nop 0
	s_nop 0
	s_nop 0
	s_nop 0
	s_nop 0
	s_nop 0
	s_nop 0
	s_nop 0
	s_nop 0
	s_nop 0
	s_nop 0
	s_nop 0
	s_nop 0
	s_nop 0
	s_nop 0
	s_nop 0
	s_nop 0
	s_nop 0
	s_nop 0
	s_nop 0
	s_nop 0
	s_nop 0
	s_nop 0
	s_nop 0
	s_nop 0
	s_nop 0
	s_nop 0
	s_nop 0
	s_nop 0
	s_nop 0
	s_nop 0
	s_nop 0
	s_nop 0
	s_nop 0
	s_nop 0
	s_nop 0
	s_nop 0
	s_nop 0
	s_nop 0
	s_nop 0
	s_nop 0
	s_nop 0
	s_nop 0
	s_nop 0
	s_nop 0
	s_nop 0
	s_nop 0
	s_nop 0
	s_nop 0
	s_nop 0
	s_nop 0
	s_nop 0
	s_nop 0
	s_nop 0
	s_nop 0
	s_nop 0
	s_nop 0
	s_nop 0
	s_nop 0
	s_nop 0
	s_nop 0
	s_nop 0
	s_nop 0
	s_nop 0
	s_nop 0
	s_nop 0
	s_nop 0
	s_nop 0
	s_nop 0
	s_nop 0
	s_nop 0
	s_nop 0
	s_nop 0
	s_nop 0
	s_nop 0
	s_nop 0
	s_nop 0
	s_nop 0
	s_nop 0
	s_nop 0
	s_nop 0
	s_nop 0
	s_nop 0
	s_nop 0
	s_nop 0
	s_nop 0
	s_nop 0
	s_nop 0
	s_nop 0
	s_nop 0
	s_nop 0
	s_nop 0
	s_nop 0
	s_nop 0
	s_nop 0
	s_nop 0
	s_nop 0
	s_nop 0
	s_nop 0
	s_nop 0
	s_nop 0
	s_nop 0
	s_nop 0
	s_nop 0
	s_nop 0
	s_nop 0
	s_nop 0
	s_nop 0
	s_nop 0
	s_nop 0
	s_nop 0
	s_nop 0
	s_nop 0
	s_nop 0
	s_nop 0
	s_nop 0
	s_nop 0
	s_nop 0
	s_nop 0
	s_nop 0
	s_nop 0
	s_nop 0
	s_nop 0
	s_nop 0
	s_nop 0
	s_nop 0
	s_nop 0
	s_nop 0
	s_nop 0
	s_nop 0
	s_nop 0
	s_nop 0
	s_nop 0
	s_nop 0
	s_nop 0
	s_nop 0
	s_nop 0
	s_nop 0
	s_nop 0
	s_nop 0
	s_nop 0
	s_nop 0
	s_nop 0
	s_nop 0
	s_nop 0
	s_nop 0
	s_nop 0
	s_nop 0
	s_nop 0
	s_nop 0
	s_nop 0
	s_nop 0
	s_nop 0
	s_nop 0
	s_nop 0
	s_nop 0
	s_nop 0
	s_nop 0
	s_nop 0
	s_nop 0
	s_nop 0
	s_nop 0
	s_nop 0
	s_nop 0
	s_nop 0
	s_nop 0
	s_nop 0
	s_nop 0
	s_nop 0
	s_nop 0
	s_nop 0
	s_nop 0
	s_nop 0
	s_nop 0
	s_nop 0
	s_nop 0
	s_nop 0
	s_nop 0
	s_nop 0
	s_nop 0
	s_nop 0
	s_nop 0
	s_nop 0
	s_nop 0
	s_nop 0
	s_nop 0
	s_nop 0
	s_nop 0
	s_nop 0
	s_nop 0
	s_nop 0
	s_nop 0
	s_nop 0
	s_nop 0
	s_nop 0
	s_nop 0
	s_nop 0
	s_nop 0
	s_nop 0
	s_nop 0
	s_nop 0
	s_nop 0
	s_nop 0
	s_nop 0
	s_nop 0
	s_nop 0
	s_nop 0
	s_nop 0
	s_nop 0
	s_nop 0
	s_nop 0
	s_nop 0
	s_nop 0
	s_nop 0
	s_nop 0
	s_nop 0
	s_nop 0
	s_nop 0
	s_nop 0
	s_nop 0
	s_nop 0
	s_nop 0
	s_nop 0
	s_nop 0
	s_nop 0
	s_nop 0
	s_nop 0
	s_nop 0
	s_nop 0
	s_nop 0
	s_nop 0
	s_nop 0
	s_nop 0
	s_nop 0
	s_nop 0
	s_nop 0
	s_nop 0
	s_nop 0
	s_nop 0
	s_nop 0
	s_nop 0
	s_nop 0
	s_nop 0
	s_nop 0
	s_nop 0
	s_nop 0
	s_nop 0
	s_nop 0
	s_nop 0
	s_nop 0
	s_nop 0
	s_nop 0
	s_nop 0
	s_nop 0
	s_nop 0
	s_nop 0
	s_nop 0
	s_nop 0
	s_nop 0
	s_nop 0
	s_nop 0
	s_nop 0
	s_nop 0
	s_nop 0
	s_nop 0
	s_nop 0
	s_nop 0
	s_nop 0
	s_nop 0
	s_nop 0
	s_nop 0
	s_nop 0
	s_nop 0
	s_nop 0
	s_nop 0
	s_nop 0
	s_nop 0
	s_nop 0
	s_nop 0
	s_nop 0
	s_nop 0
	s_nop 0
	s_nop 0
	s_nop 0
	s_nop 0
	s_nop 0
	s_nop 0
	s_nop 0
	s_nop 0
	s_nop 0
	s_nop 0
	s_nop 0
	s_nop 0
	s_nop 0
	s_nop 0
	s_nop 0
	s_nop 0
	s_nop 0
	s_nop 0
	s_nop 0
	s_nop 0
	s_nop 0
	s_nop 0
	s_nop 0
	s_nop 0
	s_nop 0
	s_nop 0
	s_nop 0
	s_nop 0
	s_nop 0
	s_nop 0
	s_nop 0
	s_nop 0
	s_nop 0
	s_nop 0
	s_nop 0
	s_nop 0
	s_nop 0
	s_nop 0
	s_nop 0
	s_nop 0
	s_nop 0
	s_nop 0
	s_nop 0
	s_nop 0
	s_nop 0
	s_nop 0
	s_nop 0
	s_nop 0
	s_nop 0
	s_nop 0
	s_nop 0
	s_nop 0
	s_nop 0
	s_nop 0
	s_nop 0
	s_nop 0
	s_nop 0
	s_nop 0
	s_nop 0
	s_nop 0
	s_nop 0
	s_nop 0
	s_nop 0
	s_nop 0
	s_nop 0
	s_nop 0
	s_nop 0
	s_nop 0
	s_nop 0
	s_nop 0
	s_nop 0
	s_nop 0
	s_nop 0
	s_nop 0
	s_nop 0
	s_nop 0
	s_nop 0
	s_nop 0
	s_nop 0
	s_nop 0
	s_nop 0
	s_nop 0
	s_nop 0
	s_nop 0
	s_nop 0
	s_nop 0
	s_nop 0
	s_nop 0
	s_nop 0
	s_nop 0
	s_nop 0
	s_nop 0
	s_nop 0
	s_nop 0
	s_nop 0
	s_nop 0
	s_nop 0
	s_nop 0
	s_nop 0
	s_nop 0
	s_nop 0
	s_nop 0
	s_nop 0
	s_nop 0
	s_nop 0
	s_nop 0
	s_nop 0
	s_nop 0
	s_nop 0
	s_nop 0
	s_nop 0
	s_nop 0
	s_nop 0
	s_nop 0
	s_nop 0
	s_nop 0
	s_nop 0
	s_nop 0
	s_nop 0
	s_nop 0
	s_nop 0
	s_nop 0
	s_nop 0
	s_nop 0
	s_nop 0
	s_nop 0
	s_nop 0
	s_nop 0
	s_nop 0
	s_nop 0
	s_nop 0
	s_nop 0
	s_nop 0
	s_nop 0
	s_nop 0
	s_nop 0
	s_nop 0
	s_nop 0
	s_nop 0
	s_nop 0
	s_nop 0
	s_nop 0
	s_nop 0
	s_nop 0
	s_nop 0
	s_nop 0
	s_nop 0
	s_nop 0
	s_nop 0
	s_nop 0
	s_nop 0
	s_nop 0
	s_nop 0
	s_nop 0
	s_nop 0
	s_nop 0
	s_nop 0
	s_nop 0
	s_nop 0
	s_nop 0
	s_nop 0
	s_nop 0
	s_nop 0
	s_nop 0
	s_nop 0
	s_nop 0
	s_nop 0
	s_nop 0
	s_nop 0
	s_nop 0
	s_nop 0
	s_nop 0
	s_nop 0
	s_nop 0
	s_nop 0
	s_nop 0
	s_nop 0
	s_nop 0
	s_nop 0
	s_nop 0
	s_nop 0
	s_nop 0
	s_nop 0
	s_nop 0
	s_nop 0
	s_nop 0
	s_nop 0
	s_nop 0
	s_nop 0
	s_nop 0
	s_nop 0
	s_nop 0
	s_nop 0
	s_nop 0
	s_nop 0
	s_nop 0
	s_nop 0
	s_nop 0
	s_nop 0
	s_nop 0
	s_nop 0
	s_nop 0
	s_nop 0
	s_nop 0
	s_nop 0
	s_nop 0
	s_nop 0
	s_nop 0
	s_nop 0
	s_nop 0
	s_nop 0
	s_nop 0
	s_nop 0
	s_nop 0
	s_nop 0
	s_nop 0
	s_nop 0
	s_nop 0
	s_nop 0
	s_nop 0
	s_nop 0
	s_nop 0
	s_nop 0
	s_nop 0
	s_nop 0
	s_nop 0
	s_nop 0
	s_nop 0
	s_nop 0
	s_nop 0
	s_nop 0
	s_nop 0
	s_nop 0
	s_nop 0
	s_nop 0
	s_nop 0
	s_nop 0
	s_nop 0
	s_nop 0
	s_nop 0
	s_nop 0
	s_nop 0
	s_nop 0
	s_nop 0
	s_nop 0
	s_nop 0
	s_nop 0
	s_nop 0
	s_nop 0
	s_nop 0
	s_nop 0
	s_nop 0
	s_nop 0
	s_nop 0
	s_nop 0
	s_nop 0
	s_nop 0
	s_nop 0
	s_nop 0
	s_nop 0
	s_nop 0
	s_nop 0
	s_nop 0
	s_nop 0
	s_nop 0
	s_nop 0
	s_nop 0
	s_nop 0
	s_nop 0
	s_nop 0
	s_nop 0
	s_nop 0
	s_nop 0
	s_nop 0
	s_nop 0
	s_nop 0
	s_nop 0
	s_nop 0
	s_nop 0
	s_nop 0
	s_nop 0
	s_nop 0
	s_nop 0
	s_nop 0
	s_nop 0
	s_nop 0
	s_nop 0
	s_nop 0
	s_nop 0
	s_nop 0
	s_nop 0
	s_nop 0
	s_nop 0
	s_nop 0
	s_nop 0
	s_nop 0
	s_nop 0
	s_nop 0
	s_nop 0
	s_nop 0
	s_nop 0
	s_nop 0
	s_nop 0
	s_nop 0
	s_nop 0
	s_nop 0
	s_nop 0
	s_nop 0
	s_nop 0
	s_nop 0
	s_nop 0
	s_nop 0
	s_nop 0
	s_nop 0
	s_nop 0
	s_nop 0
	s_nop 0
	s_nop 0
	s_nop 0
	s_nop 0
	s_nop 0
	s_nop 0
	s_nop 0
	s_nop 0
	s_nop 0
	s_nop 0
	s_nop 0
	s_nop 0
	s_nop 0
	s_nop 0
	s_nop 0
	s_nop 0
	s_nop 0
	s_nop 0
	s_nop 0
	s_nop 0
	s_nop 0
	s_nop 0
	s_nop 0
	s_nop 0
	s_nop 0
	s_nop 0
	s_nop 0
	s_nop 0
	s_nop 0
	s_nop 0
	s_nop 0
	s_nop 0
	s_nop 0
	s_nop 0
	s_nop 0
	s_nop 0
	s_nop 0
	s_nop 0
	s_nop 0
	s_nop 0
	s_nop 0
	s_nop 0
	s_nop 0
	s_nop 0
	s_nop 0
	s_nop 0
.LBB0_750:
	s_waitcnt vmcnt(0)
	s_waitcnt lgkmcnt(0)
	s_barrier
	s_and_saveexec_b64 s[0:1], s[56:57]
	s_cbranch_execz .LBB0_802
	s_add_i32 s3, 0, 0x27fc0
	s_waitcnt vmcnt(15)
	v_mov_b32_e32 v0, s3
	s_waitcnt vmcnt(0) expcnt(0) lgkmcnt(0)
	ds_read_b32 v2, v0
	s_add_i32 s3, 0, 0x27fc4
	v_mov_b32_e32 v0, s3
	ds_read_b32 v0, v0
	s_waitcnt lgkmcnt(1)
	v_cmp_ne_u32_e32 vcc, 0, v2
	s_cbranch_vccnz .LBB0_766
	s_add_u32 s4, s28, 0x1000
	s_addc_u32 s5, s29, 0
	s_add_u32 s6, s28, 0x1100
	s_addc_u32 s7, s29, 0
	s_add_u32 s8, s28, 0x1200
	v_readlane_b32 s3, v254, 8
	s_addc_u32 s9, s29, 0
	s_mul_i32 s3, s31, s3
	s_add_u32 s10, s28, 0x1300
	s_mul_i32 s3, s3, s30
	s_addc_u32 s11, s29, 0
	s_mov_b32 s16, 1
	v_mov_b32_e32 v16, 0
	s_branch .LBB0_754
